# P5 entry waits for its first panel only; second panel's phase-4 counter awaited inside unit 0's last K iteration
# baseline (speedup 1.0000x reference)
.LBB0_537:
	s_or_b64 exec, exec, s[0:1]
	s_and_b64 s[0:1], s[36:37], exec
	s_cselect_b32 s28, 16, 0x1000
	s_add_u32 s64, s76, 0x13d00000
	s_addc_u32 s65, s77, 0
	s_bfe_u32 s68, s96, 0x20006
	s_mul_i32 s0, s68, 0x3700
	s_add_i32 s71, s0, 0
	s_and_b32 s0, s96, 0xffffff00
	s_lshr_b32 s74, s96, 8
	s_add_i32 s84, s0, 0
	s_lshl_b32 s11, s74, 5
	s_add_i32 s80, s84, 0x12600
	s_cmpk_lt_u32 s96, 0x540
	v_readlane_b32 s20, v255, 31
	s_cselect_b64 s[40:41], -1, 0
	s_add_i32 s12, s20, -4
	s_lshl_b32 s13, s12, 2
	s_lshl_b32 s22, s12, 10
	s_cmpk_lt_u32 s96, 0x440
	s_cselect_b64 s[42:43], -1, 0
	s_lshl_b32 s66, s20, 10
	s_cmpk_lt_u32 s96, 0x340
	s_cselect_b64 s[46:47], -1, 0
	s_add_i32 s14, s20, 4
	s_lshl_b32 s15, s14, 2
	s_lshl_b32 s23, s14, 10
	s_cmpk_lt_u32 s96, 0x240
	s_cselect_b64 s[48:49], -1, 0
	s_add_i32 s16, s20, 8
	s_lshl_b32 s17, s16, 2
	s_lshl_b32 s24, s16, 10
	s_cmp_eq_u32 s20, 4
	s_cselect_b64 s[50:51], -1, 0
	s_cmp_eq_u32 s20, 2
	s_mov_b32 s0, 0xfc00000
	s_cselect_b32 s38, s0, 0x13d00000
	s_add_u32 s8, s76, s6
	s_addc_u32 s9, s77, 0
	s_mul_i32 s0, s20, 0x2400
	s_add_i32 s1, 0, 0x1a900
	s_add_i32 s81, s1, s0
	s_lshl_b32 s0, s74, 7
	s_add_i32 s83, s0, 0
	s_add_i32 s82, s81, 0x2000
	s_add_i32 s83, s83, 0x14800
	s_add_i32 s84, s84, 0x12400
	s_lshl_b32 s29, s20, 5
	s_add_u32 s6, s64, s6
	s_addc_u32 s7, s65, 0
	s_lshl_b32 s85, s33, 10
	s_add_u32 s18, s76, 0x10000
	v_writelane_b32 v255, s96, 33
	s_addc_u32 s19, s77, 0
	v_lshl_or_b32 v11, s68, 4, v9
	v_writelane_b32 v255, s18, 34
	v_add_u32_e32 v25, 1, v11
	v_lshlrev_b32_e32 v27, 3, v38
	v_writelane_b32 v255, s19, 35
	v_lshlrev_b32_e32 v10, 7, v25
	v_and_b32_e32 v22, 8, v27
	s_add_i32 s0, 0, 0x1cd00
	s_add_i32 s18, 0, 0x1f100
	v_add3_u32 v91, s1, v10, v22
	v_add3_u32 v92, s0, v10, v22
	v_add3_u32 v93, s18, v10, v22
	v_lshlrev_b32_e32 v10, 8, v25
	s_add_i32 s19, 0, 0x23900
	v_add3_u32 v28, s19, v10, v22
	v_lshlrev_b32_e32 v10, 7, v11
	v_add3_u32 v94, s1, v10, v22
	v_add3_u32 v95, s0, v10, v22
	v_add3_u32 v96, s18, v10, v22
	v_lshlrev_b32_e32 v10, 8, v11
	v_add3_u32 v29, s19, v10, v22
	v_add_u32_e32 v10, 1, v89
	s_add_i32 s19, 0, 0x21500
	v_lshl_add_u32 v32, v10, 7, s19
	v_xor_b32_e32 v10, v10, v39
	v_lshlrev_b32_e32 v10, 4, v10
	v_and_b32_e32 v33, 0x70, v10
	v_lshlrev_b32_e32 v10, 7, v89
	v_add_u32_e32 v34, s19, v10
	s_add_i32 s19, 0, 0x12800
	s_cmp_lg_u32 s12, 16
	v_add_u32_e32 v36, s19, v10
	v_or_b32_e32 v10, s13, v38
	s_cselect_b64 vcc, -1, 0
	v_xor_b32_e32 v22, v89, v39
	v_cndmask_b32_e32 v98, 64, v10, vcc
	v_bitop3_b32 v10, v38, v39, s13 bitop3:0x36
	v_lshlrev_b32_e32 v22, 4, v22
	v_and_or_b32 v10, v10, 7, v41
	v_and_b32_e32 v35, 0x70, v22
	v_lshlrev_b32_e32 v22, 4, v10
	v_mov_b32_e32 v10, 0
	v_mov_b32_e32 v23, v10
	s_cmp_lg_u32 s20, 16
	v_lshl_add_u64 v[48:49], s[4:5], 0, v[22:23]
	v_or_b32_e32 v22, s3, v38
	s_cselect_b64 vcc, -1, 0
	v_cndmask_b32_e32 v99, 64, v22, vcc
	v_bitop3_b32 v22, v38, v39, s3 bitop3:0x36
	v_and_or_b32 v22, v22, 7, v41
	v_lshlrev_b32_e32 v22, 4, v22
	s_cmp_lg_u32 s14, 16
	v_lshl_add_u64 v[50:51], s[4:5], 0, v[22:23]
	v_or_b32_e32 v22, s15, v38
	s_cselect_b64 vcc, -1, 0
	v_cndmask_b32_e32 v100, 64, v22, vcc
	v_bitop3_b32 v22, v38, v39, s15 bitop3:0x36
	v_and_or_b32 v22, v22, 7, v41
	v_lshlrev_b32_e32 v22, 4, v22
	s_cmp_lg_u32 s16, 16
	v_lshl_add_u64 v[52:53], s[4:5], 0, v[22:23]
	v_or_b32_e32 v22, s17, v38
	s_cselect_b64 vcc, -1, 0
	v_cndmask_b32_e32 v101, 64, v22, vcc
	v_bitop3_b32 v22, v38, v39, s17 bitop3:0x36
	v_and_or_b32 v22, v22, 7, v41
	v_lshlrev_b32_e32 v22, 4, v22
	v_lshl_add_u64 v[54:55], s[4:5], 0, v[22:23]
	v_xor_b32_e32 v22, v38, v20
	s_movk_i32 s10, 0x3700
	v_or_b32_e32 v22, v22, v41
	v_lshlrev_b32_e32 v41, 5, v9
	v_lshrrev_b32_e32 v45, 7, v42
	v_cmp_gt_u32_e64 s[0:1], 16, v40
	v_or_b32_e32 v103, v27, v41
	v_lshl_add_u32 v104, v40, 2, s71
	v_add_u32_e32 v40, s71, v41
	v_lshrrev_b32_e32 v41, 2, v9
	v_mul_lo_u32 v45, v45, s10
	v_or_b32_e32 v41, v90, v41
	v_add_u32_e32 v67, 0, v45
	v_bfe_u32 v45, v42, 3, 4
	v_mul_u32_u24_e32 v41, 0x48, v41
	v_and_b32_e32 v21, 12, v21
	v_mul_u32_u24_e32 v45, 0x48, v45
	v_or_b32_e32 v24, s11, v90
	v_add_lshl_u32 v105, v21, v41, 1
	v_lshl_or_b32 v21, v89, 6, v8
	v_add_lshl_u32 v8, v45, v8, 1
	v_mov_b32_e32 v45, v10
	v_and_b32_e32 v26, 7, v25
	v_lshl_add_u64 v[60:61], s[6:7], 0, v[44:45]
	v_cmp_eq_u32_e64 s[6:7], 0, v42
	v_lshrrev_b32_e32 v42, 3, v24
	v_and_b32_e32 v62, 8, v42
	v_bitop3_b32 v63, v42, v26, 5 bitop3:0x6c
	v_or_b32_e32 v63, v63, v62
	v_lshlrev_b32_e32 v68, 4, v63
	v_add_u32_e32 v63, 64, v24
	v_bitop3_b32 v45, v42, v25, 7 bitop3:0x78
	v_lshrrev_b32_e32 v64, 3, v63
	v_xor_b32_e32 v69, v42, v20
	v_bitop3_b32 v42, v42, v20, 5 bitop3:0x6c
	v_and_b32_e32 v65, 8, v64
	v_or_b32_e32 v42, v42, v62
	v_bitop3_b32 v62, v64, v20, 5 bitop3:0x6c
	v_or_b32_e32 v62, v62, v65
	v_lshlrev_b32_e32 v108, 4, v69
	v_lshlrev_b32_e32 v69, 4, v62
	v_or_b32_e32 v62, 16, v24
	v_lshlrev_b32_e32 v22, 4, v22
	v_lshlrev_b32_e32 v71, 1, v63
	v_lshrrev_b32_e32 v63, 3, v62
	v_lshl_add_u64 v[56:57], s[4:5], 0, v[22:23]
	v_xor_b32_e32 v22, v88, v20
	v_bitop3_b32 v26, v64, v26, 5 bitop3:0x6c
	v_bitop3_b32 v64, v63, v25, 7 bitop3:0x78
	v_lshlrev_b32_e32 v22, 4, v22
	v_or_b32_e32 v26, v26, v65
	v_lshlrev_b32_e32 v111, 4, v64
	v_and_b32_e32 v64, 8, v63
	v_bitop3_b32 v65, v63, v25, 7 bitop3:0x28
	s_movk_i32 s18, 0x48
	v_lshl_add_u64 v[58:59], s[8:9], 0, v[22:23]
	v_or_b32_e32 v23, s11, v9
	v_or_b32_e32 v65, v65, v64
	v_mul_u32_u24_e32 v30, 0x48, v11
	v_mul_u32_u24_e32 v31, 0x48, v9
	v_lshlrev_b32_e32 v97, 2, v11
	v_or_b32_e32 v22, 16, v90
	v_lshlrev_b32_e32 v72, 4, v65
	v_add_u32_e32 v65, 0x50, v24
	v_mul_lo_u32 v23, v23, s18
	v_mad_u32_u24 v11, v11, s18, 32
	v_lshlrev_b32_e32 v70, 1, v24
	v_add_lshl_u32 v109, v24, v30, 1
	v_add_lshl_u32 v110, v24, v31, 1
	v_lshrrev_b32_e32 v73, 3, v65
	v_xor_b32_e32 v75, v63, v20
	v_bitop3_b32 v63, v63, v20, 7 bitop3:0x6c
	v_add_lshl_u32 v113, v62, v30, 1
	v_add_lshl_u32 v115, v30, v90, 1
	v_add_lshl_u32 v116, v22, v30, 1
	v_add_u32_e32 v30, 0x480, v23
	v_add_lshl_u32 v119, v11, v90, 1
	v_add_lshl_u32 v120, v11, v22, 1
	v_or_b32_e32 v11, 32, v90
	v_lshlrev_b32_e32 v123, 2, v24
	v_or_b32_e32 v24, 1, v90
	v_cmp_eq_u32_e32 vcc, v90, v9
	v_lshlrev_b32_e32 v106, 5, v20
	v_and_b32_e32 v74, 8, v73
	v_bitop3_b32 v25, v73, v25, 7 bitop3:0x28
	v_or_b32_e32 v63, v63, v64
	v_bitop3_b32 v20, v73, v20, 7 bitop3:0x6c
	v_lshlrev_b32_e32 v73, 1, v62
	v_add_lshl_u32 v114, v62, v31, 1
	v_add_lshl_u32 v118, v30, v90, 1
	v_add_lshl_u32 v122, v11, v30, 1
	v_lshlrev_b32_e32 v124, 2, v62
	v_or_b32_e32 v30, 2, v90
	v_cndmask_b32_e64 v62, 0, 1.0, vcc
	v_cmp_eq_u32_e32 vcc, v24, v9
	v_lshlrev_b32_e32 v112, 4, v75
	v_lshlrev_b32_e32 v75, 4, v63
	v_add_lshl_u32 v117, v90, v23, 1
	v_add_lshl_u32 v121, v11, v23, 1
	v_add_lshl_u32 v125, v90, v31, 1
	v_add_lshl_u32 v23, v11, v31, 1
	v_or_b32_e32 v31, 3, v90
	v_cndmask_b32_e64 v63, 0, 1.0, vcc
	v_cmp_eq_u32_e32 vcc, v30, v9
	v_cmp_eq_u32_e64 s[4:5], 0, v9
	v_mad_u32_u24 v37, v9, s18, 16
	v_cmp_lt_u32_e64 s[8:9], v90, v9
	v_cmp_gt_u32_e64 s[10:11], v90, v9
	v_cmp_lt_u32_e64 s[12:13], v24, v9
	v_cmp_lt_u32_e64 s[14:15], v30, v9
	v_cmp_gt_u32_e64 s[16:17], v30, v9
	v_cmp_lt_u32_e64 s[18:19], v31, v9
	v_cmp_gt_u32_e64 s[20:21], v31, v9
	v_cndmask_b32_e64 v64, 0, 1.0, vcc
	v_cmp_eq_u32_e32 vcc, v31, v9
	v_lshlrev_b32_e32 v9, 2, v9
	v_lshl_add_u32 v24, v38, 10, s97
	s_mov_b32 s3, 0xdc00
	v_add3_u32 v126, v24, v9, s3
	v_and_b32_e32 v9, 3, v39
	s_movk_i32 s25, 0x2400
	v_lshlrev_b32_e32 v43, 2, v21
	v_lshlrev_b32_e32 v21, 1, v21
	v_lshl_or_b32 v9, v9, 3, s29
	v_lshlrev_b32_e32 v24, 1, v41
	s_waitcnt lgkmcnt(0)
	s_barrier
	v_lshlrev_b32_e32 v66, 2, v89
	v_or_b32_e32 v25, v25, v74
	v_or_b32_e32 v20, v20, v74
	v_add3_u32 v128, v9, v24, s25
	v_mov_b32_e32 v9, 0x3540
	v_add_u32_e32 v151, v67, v8
	v_add_u32_e32 v8, 0, v21
	s_mov_b32 s39, 0
	v_and_b32_e32 v102, 48, v39
	v_lshlrev_b32_e32 v26, 4, v26
	v_lshlrev_b32_e32 v42, 4, v42
	v_lshlrev_b32_e32 v25, 4, v25
	v_lshlrev_b32_e32 v20, 4, v20
	v_lshlrev_b32_e32 v74, 1, v65
	v_add_lshl_u32 v22, v37, v90, 1
	v_add_lshl_u32 v11, v11, v37, 1
	v_writelane_b32 v255, s97, 32
	v_lshl_or_b32 v129, v38, 4, v9
	s_add_i32 s3, 0, 0x15c00
	s_add_i32 s88, s22, 0
	s_add_i32 s89, s23, 0
	s_add_i32 s90, s24, 0
	v_add_u32_e32 v9, 0, v66
	v_add_u32_e32 v152, 0x12800, v8
	v_mbcnt_lo_u32_b32 v8, -1, 0
	s_mov_b64 s[52:53], s[38:39]
	v_add_u32_e32 v107, s70, v89
	v_lshlrev_b32_e32 v45, 4, v45
	v_cndmask_b32_e64 v65, 0, 1.0, vcc
	v_add_u32_e32 v127, 0x2d00, v103
	v_writelane_b32 v255, s29, 44
	v_or_b32_e32 v130, 0x3500, v102
	v_add_u32_e32 v131, v28, v68
	v_add_u32_e32 v132, v28, v26
	v_add_u32_e32 v133, v29, v42
	v_add_u32_e32 v134, v29, v69
	v_add_u32_e32 v135, s3, v70
	v_add_u32_e32 v136, s3, v71
	s_mov_b32 s86, 0x4038aa3b
	s_add_i32 s67, 0, 0x10000
	v_add_u32_e32 v137, v28, v72
	v_add_u32_e32 v138, v28, v25
	v_add_u32_e32 v139, v29, v75
	v_add_u32_e32 v140, v29, v20
	v_add_u32_e32 v141, s3, v73
	v_add_u32_e32 v142, s3, v74
	v_add_u32_e32 v143, v32, v33
	v_add_u32_e32 v145, v34, v35
	s_mov_b32 s87, 0xbfb8aa3b
	v_add_u32_e32 v146, v36, v44
	s_add_i32 s88, s88, 0x23900
	s_add_i32 s89, s89, 0x23900
	s_add_i32 s90, s90, 0x23900
	s_add_i32 s91, 0, 0x27900
	s_add_i32 s92, s81, 0x400
	s_add_i32 s93, s81, 0x800
	s_add_i32 s94, s81, 0xc00
	s_add_i32 s95, s81, 0x1400
	s_add_i32 s96, s81, 0x1800
	s_add_i32 s97, s81, 0x1c00
	s_add_i32 s3, 0, 0x16100
	s_add_i32 s69, 0, 0x18500
	v_mov_b32_e32 v147, 0xbf92477c
	v_add_u32_e32 v148, v40, v27
	s_xor_b64 s[54:55], s[26:27], -1
	v_add_u32_e32 v149, 0, v43
	v_add_u32_e32 v150, 0x12400, v9
	v_mov_b32_e32 v153, 0x3a27c5ac
	v_mbcnt_hi_u32_b32 v144, -1, v8
	v_add_u32_e32 v154, s71, v22
	v_add_u32_e32 v155, s71, v23
	v_add_u32_e32 v156, s71, v11
	s_mov_b32 s33, s28
	s_mov_b32 s29, 0
	v_add_u32_e32 v232, s69, v118
	v_add_u32_e32 v216, v94, v112
	v_add_u32_e32 v235, s3, v121
	v_add_u32_e32 v210, v96, v108
	v_xor_b32_e32 v242, 16, v144
	v_and_b32_e32 v241, 64, v144
	v_add_u32_e32 v21, 64, v241
	v_cmp_lt_i32_e32 vcc, v242, v21
	s_nop 1
	v_cndmask_b32_e32 v20, v144, v242, vcc
	v_lshlrev_b32_e32 v221, 2, v20
	v_add_u32_e32 v226, s83, v102
	v_add_u32_e32 v209, v95, v108
	v_add_u32_e32 v234, s67, v120
	v_add_u32_e32 v217, v95, v112
	v_add_u32_e32 v225, 0x15d80, v44
	v_add_u32_e32 v230, s69, v117
	v_or_b32_e32 v240, v102, v241
	v_add_u32_e32 v227, s67, v115
	v_add_u32_e32 v207, v92, v45
	v_add_u32_e32 v213, s67, v109
	v_add_u32_e32 v218, v96, v112
	v_add_u32_e32 v231, s3, v118
	v_add_u32_e32 v219, v93, v111
	v_add_u32_e32 v233, s67, v119
	v_add_u32_e32 v236, s69, v121
	v_add_u32_e32 v220, v91, v111
	v_add_u32_e32 v224, s71, v114
	v_add_u32_e32 v228, s67, v116
	v_xor_b32_e32 v243, 32, v144
	v_cmp_lt_i32_e32 vcc, v243, v21
	s_nop 1
	v_cndmask_b32_e32 v22, v144, v243, vcc
	v_lshlrev_b32_e32 v222, 2, v22
	v_add_u32_e32 v239, 0x12600, v97
	v_add_u32_e32 v238, s69, v122
	v_add_u32_e32 v215, v92, v111
	v_add_u32_e32 v212, v91, v45
	v_add_u32_e32 v208, v94, v108
	v_add_u32_e32 v237, s3, v122
	v_add_u32_e32 v229, s3, v117
	v_add_u32_e32 v223, s67, v113
	v_add_u32_e32 v214, s71, v110
	v_add_u32_e32 v211, v93, v45
	s_waitcnt vmcnt(0)

.LBB0_1389:
	s_waitcnt lgkmcnt(0)
	global_load_dword v1, v0, s[4:5] sc1
	s_mov_b64 s[6:7], -1
	s_mov_b64 s[8:9], -1
	s_waitcnt vmcnt(0)
	v_cmp_gt_u32_e32 vcc, 4, v1
	s_cbranch_vccnz .LBB0_1391
	global_load_dword v1, v0, s[4:5] sc1
	s_waitcnt vmcnt(0)
	v_cmp_gt_u32_e64 s[8:9], 4, v1
.LBB0_1391:
	s_andn2_b64 vcc, exec, s[8:9]
	s_cbranch_vccnz .LBB0_1388
	s_cmp_lg_u32 s3, 0
	s_sleep 8
	s_cbranch_scc0 .LBB0_1387
	global_load_dword v1, v0, s[4:5] sc1
	s_waitcnt vmcnt(0)
	v_cmp_lt_u32_e32 vcc, 3, v1
	v_cmp_gt_u32_e64 s[6:7], 4, v1
	s_cbranch_vccz .LBB0_1395
	global_load_dword v1, v0, s[4:5] sc1
	s_waitcnt vmcnt(0)
	v_cmp_gt_u32_e64 s[6:7], 4, v1
.LBB0_1395:
	s_andn2_b64 vcc, exec, s[6:7]
	s_mov_b64 s[6:7], -1
	s_cbranch_vccnz .LBB0_1388
	s_sleep 8
	global_load_dword v1, v0, s[4:5] sc1
	s_waitcnt vmcnt(0)
	v_cmp_lt_u32_e32 vcc, 3, v1
	v_cmp_gt_u32_e64 s[6:7], 4, v1
	s_cbranch_vccz .LBB0_1398
	global_load_dword v1, v0, s[4:5] sc1
	s_waitcnt vmcnt(0)
	v_cmp_gt_u32_e64 s[6:7], 4, v1

.LBB0_1429:
	s_cmp_eq_u32 s51, 12
	s_cbranch_scc0 .Lp5a_nowait
	s_cmp_eq_u32 s45, 1
	s_cbranch_scc0 .Lp5a_nowait
	s_lshl_b32 vcc_lo, s2, 4
	s_and_b32 vcc_lo, vcc_lo, 0x70
	s_bfe_u32 vcc_hi, s2, 0x30003
	s_or_b32 vcc_lo, vcc_lo, vcc_hi
	s_lshl_b32 vcc_lo, vcc_lo, 8
	s_add_i32 vcc_lo, vcc_lo, 0x20800
	v_mov_b32_e32 v240, vcc_lo
	s_mov_b32 m0, 0x10000
.Lp5a_poll:
	global_load_dword v241, v240, s[76:77] sc1
	s_waitcnt vmcnt(0)
	v_cmp_lt_u32_e32 vcc, 3, v241
	s_cbranch_vccnz .Lp5a_ready
	s_sleep 8
	s_sub_u32 m0, m0, 1
	s_cmp_eq_u32 m0, 0
	s_cbranch_scc0 .Lp5a_poll
.Lp5a_ready:
	buffer_inv sc1
.Lp5a_nowait:
	ds_read_b128 v[158:161], v151
	ds_read_b128 v[162:165], v151 offset:1024
	ds_read_b128 v[166:169], v151 offset:2048
	ds_read_b128 v[170:173], v151 offset:3072
	ds_read_b128 v[174:177], v152
	ds_read_b128 v[178:181], v152 offset:1024
	ds_read_b128 v[182:185], v152 offset:2048
	ds_read_b128 v[186:189], v152 offset:3072
	s_add_u32 s30, s22, 0xfffc0080
	s_addc_u32 s31, s23, -1
	s_cmp_eq_u32 s51, 12
	s_cselect_b32 s35, s17, s31
	s_cselect_b32 s34, s16, s30
	s_cselect_b32 s31, s19, s15
	s_cselect_b32 s30, s18, s13
	v_lshl_add_u64 v[222:223], s[22:23], 0, v[138:139]
	s_add_i32 m0, s21, 0xc000
	ds_read_b128 v[190:193], v153
	ds_read_b128 v[194:197], v153 offset:1024
	ds_read_b128 v[198:201], v153 offset:2048
	ds_read_b128 v[202:205], v153 offset:3072
	ds_read_b128 v[206:209], v153 offset:4096
	ds_read_b128 v[210:213], v153 offset:5120
	ds_read_b128 v[214:217], v153 offset:6144
	ds_read_b128 v[218:221], v153 offset:7168
	global_load_lds_dwordx4 v[222:223], off
	v_lshl_add_u64 v[222:223], s[22:23], 0, v[140:141]
	s_add_i32 m0, s21, 0xe000
	s_nop 0
	global_load_lds_dwordx4 v[222:223], off
	s_waitcnt vmcnt(8)
	s_waitcnt lgkmcnt(0)
	s_barrier
	s_setprio 1
	s_waitcnt lgkmcnt(0)
	v_mfma_f32_16x16x32_f16 v[124:127], v[158:161], v[190:193], v[124:127]
	v_mfma_f32_16x16x32_f16 v[120:123], v[166:169], v[190:193], v[120:123]
	v_mfma_f32_16x16x32_f16 v[108:111], v[158:161], v[198:201], v[108:111]
	v_mfma_f32_16x16x32_f16 v[104:107], v[166:169], v[198:201], v[104:107]
	v_mfma_f32_16x16x32_f16 v[92:95], v[158:161], v[206:209], v[92:95]
	v_mfma_f32_16x16x32_f16 v[88:91], v[166:169], v[206:209], v[88:91]
	v_mfma_f32_16x16x32_f16 v[76:79], v[158:161], v[214:217], v[76:79]
	v_mfma_f32_16x16x32_f16 v[72:75], v[166:169], v[214:217], v[72:75]
	v_mfma_f32_16x16x32_f16 v[124:127], v[162:165], v[194:197], v[124:127]
	v_mfma_f32_16x16x32_f16 v[120:123], v[170:173], v[194:197], v[120:123]
	v_mfma_f32_16x16x32_f16 v[108:111], v[162:165], v[202:205], v[108:111]
	v_mfma_f32_16x16x32_f16 v[104:107], v[170:173], v[202:205], v[104:107]
	v_mfma_f32_16x16x32_f16 v[92:95], v[162:165], v[210:213], v[92:95]
	v_mfma_f32_16x16x32_f16 v[88:91], v[170:173], v[210:213], v[88:91]
	v_mfma_f32_16x16x32_f16 v[76:79], v[162:165], v[218:221], v[76:79]
	v_mfma_f32_16x16x32_f16 v[72:75], v[170:173], v[218:221], v[72:75]
	s_setprio 0
	s_setprio 1
	v_mfma_f32_16x16x32_f16 v[116:119], v[174:177], v[190:193], v[116:119]
	v_mfma_f32_16x16x32_f16 v[112:115], v[182:185], v[190:193], v[112:115]
	v_mfma_f32_16x16x32_f16 v[100:103], v[174:177], v[198:201], v[100:103]
	v_mfma_f32_16x16x32_f16 v[96:99], v[182:185], v[198:201], v[96:99]
	v_mfma_f32_16x16x32_f16 v[84:87], v[174:177], v[206:209], v[84:87]
	v_mfma_f32_16x16x32_f16 v[80:83], v[182:185], v[206:209], v[80:83]
	v_mfma_f32_16x16x32_f16 v[68:71], v[174:177], v[214:217], v[68:71]
	v_mfma_f32_16x16x32_f16 v[64:67], v[182:185], v[214:217], v[64:67]
	v_mfma_f32_16x16x32_f16 v[116:119], v[178:181], v[194:197], v[116:119]
	v_mfma_f32_16x16x32_f16 v[112:115], v[186:189], v[194:197], v[112:115]
	v_mfma_f32_16x16x32_f16 v[100:103], v[178:181], v[202:205], v[100:103]
	v_mfma_f32_16x16x32_f16 v[96:99], v[186:189], v[202:205], v[96:99]
	v_mfma_f32_16x16x32_f16 v[84:87], v[178:181], v[210:213], v[84:87]
	v_mfma_f32_16x16x32_f16 v[80:83], v[186:189], v[210:213], v[80:83]
	v_mfma_f32_16x16x32_f16 v[68:71], v[178:181], v[218:221], v[68:71]
	v_mfma_f32_16x16x32_f16 v[64:67], v[186:189], v[218:221], v[64:67]
	s_setprio 0
	s_barrier
	s_add_i32 s52, s46, s3
	v_lshl_add_u64 v[222:223], s[30:31], 0, v[132:133]
	s_mov_b32 m0, s52
	ds_read_b128 v[190:193], v153 offset:16384
	ds_read_b128 v[194:197], v153 offset:17408
	ds_read_b128 v[198:201], v153 offset:18432
	ds_read_b128 v[202:205], v153 offset:19456
	ds_read_b128 v[206:209], v153 offset:20480
	ds_read_b128 v[210:213], v153 offset:21504
	ds_read_b128 v[214:217], v153 offset:22528
	ds_read_b128 v[218:221], v153 offset:23552
	global_load_lds_dwordx4 v[222:223], off
	s_add_i32 m0, s52, 0x2000
	s_add_u32 s52, s30, 0x40000
	v_lshl_add_u64 v[224:225], s[30:31], 0, v[128:129]
	s_addc_u32 s53, s31, 0
	s_add_i32 s54, s47, s3
	global_load_lds_dwordx4 v[224:225], off
	v_lshl_add_u64 v[226:227], s[52:53], 0, v[132:133]
	s_mov_b32 m0, s54
	v_lshl_add_u64 v[228:229], s[34:35], 0, v[130:131]
	global_load_lds_dwordx4 v[226:227], off
	v_lshl_add_u64 v[226:227], s[52:53], 0, v[128:129]
	s_add_i32 m0, s54, 0x2000
	s_nop 0
	global_load_lds_dwordx4 v[226:227], off
	v_lshl_add_u64 v[226:227], s[34:35], 0, v[134:135]
	s_mov_b32 m0, s21
	s_nop 0
	global_load_lds_dwordx4 v[226:227], off
	s_mov_b32 m0, s40
	s_nop 0
	global_load_lds_dwordx4 v[228:229], off
	s_waitcnt vmcnt(8)
	s_waitcnt lgkmcnt(0)
	s_barrier
	s_setprio 1
	s_waitcnt lgkmcnt(0)
	v_mfma_f32_16x16x32_f16 v[60:63], v[158:161], v[190:193], v[60:63]
	v_mfma_f32_16x16x32_f16 v[56:59], v[166:169], v[190:193], v[56:59]
	v_mfma_f32_16x16x32_f16 v[44:47], v[158:161], v[198:201], v[44:47]
	v_mfma_f32_16x16x32_f16 v[40:43], v[166:169], v[198:201], v[40:43]
	v_mfma_f32_16x16x32_f16 v[28:31], v[158:161], v[206:209], v[28:31]
	v_mfma_f32_16x16x32_f16 v[24:27], v[166:169], v[206:209], v[24:27]
	v_mfma_f32_16x16x32_f16 v[12:15], v[158:161], v[214:217], v[12:15]
	v_mfma_f32_16x16x32_f16 v[8:11], v[166:169], v[214:217], v[8:11]
	v_mfma_f32_16x16x32_f16 v[60:63], v[162:165], v[194:197], v[60:63]
	v_mfma_f32_16x16x32_f16 v[56:59], v[170:173], v[194:197], v[56:59]
	v_mfma_f32_16x16x32_f16 v[44:47], v[162:165], v[202:205], v[44:47]
	v_mfma_f32_16x16x32_f16 v[40:43], v[170:173], v[202:205], v[40:43]
	v_mfma_f32_16x16x32_f16 v[28:31], v[162:165], v[210:213], v[28:31]
	v_mfma_f32_16x16x32_f16 v[24:27], v[170:173], v[210:213], v[24:27]
	v_mfma_f32_16x16x32_f16 v[12:15], v[162:165], v[218:221], v[12:15]
	v_mfma_f32_16x16x32_f16 v[8:11], v[170:173], v[218:221], v[8:11]
	s_setprio 0
	s_setprio 1
	v_mfma_f32_16x16x32_f16 v[52:55], v[174:177], v[190:193], v[52:55]
	v_mfma_f32_16x16x32_f16 v[48:51], v[182:185], v[190:193], v[48:51]
	v_mfma_f32_16x16x32_f16 v[36:39], v[174:177], v[198:201], v[36:39]
	v_mfma_f32_16x16x32_f16 v[32:35], v[182:185], v[198:201], v[32:35]
	v_mfma_f32_16x16x32_f16 v[20:23], v[174:177], v[206:209], v[20:23]
	v_mfma_f32_16x16x32_f16 v[16:19], v[182:185], v[206:209], v[16:19]
	v_mfma_f32_16x16x32_f16 v[4:7], v[174:177], v[214:217], v[4:7]
	v_mfma_f32_16x16x32_f16 v[0:3], v[182:185], v[214:217], v[0:3]
	v_mfma_f32_16x16x32_f16 v[52:55], v[178:181], v[194:197], v[52:55]
	v_mfma_f32_16x16x32_f16 v[48:51], v[186:189], v[194:197], v[48:51]
	v_mfma_f32_16x16x32_f16 v[36:39], v[178:181], v[202:205], v[36:39]
	v_mfma_f32_16x16x32_f16 v[32:35], v[186:189], v[202:205], v[32:35]
	v_mfma_f32_16x16x32_f16 v[20:23], v[178:181], v[210:213], v[20:23]
	v_mfma_f32_16x16x32_f16 v[16:19], v[186:189], v[210:213], v[16:19]
	v_mfma_f32_16x16x32_f16 v[4:7], v[178:181], v[218:221], v[4:7]
	v_mfma_f32_16x16x32_f16 v[0:3], v[186:189], v[218:221], v[0:3]
	s_setprio 0
	s_barrier
	ds_read_b128 v[158:161], v154
	ds_read_b128 v[162:165], v154 offset:1024
	ds_read_b128 v[166:169], v154 offset:2048
	ds_read_b128 v[170:173], v154 offset:3072
	ds_read_b128 v[174:177], v155
	ds_read_b128 v[178:181], v155 offset:1024
	ds_read_b128 v[182:185], v155 offset:2048
	ds_read_b128 v[186:189], v155 offset:3072
	s_add_u32 s34, s34, 0x40000
	s_addc_u32 s35, s35, 0
	s_mov_b32 m0, s41
	v_lshl_add_u64 v[230:231], s[34:35], 0, v[134:135]
	ds_read_b128 v[190:193], v153 offset:32768
	ds_read_b128 v[194:197], v153 offset:33792
	ds_read_b128 v[198:201], v153 offset:34816
	ds_read_b128 v[202:205], v153 offset:35840
	ds_read_b128 v[206:209], v153 offset:36864
	ds_read_b128 v[210:213], v153 offset:37888
	ds_read_b128 v[214:217], v153 offset:38912
	ds_read_b128 v[218:221], v153 offset:39936
	global_load_lds_dwordx4 v[230:231], off
	v_lshl_add_u64 v[230:231], s[34:35], 0, v[130:131]
	s_mov_b32 m0, s42
	s_nop 0
	global_load_lds_dwordx4 v[230:231], off
	s_waitcnt vmcnt(8)
	s_waitcnt lgkmcnt(0)
	s_barrier
	s_setprio 1
	s_waitcnt lgkmcnt(0)
	v_mfma_f32_16x16x32_f16 v[124:127], v[158:161], v[190:193], v[124:127]
	v_mfma_f32_16x16x32_f16 v[120:123], v[166:169], v[190:193], v[120:123]
	v_mfma_f32_16x16x32_f16 v[108:111], v[158:161], v[198:201], v[108:111]
	v_mfma_f32_16x16x32_f16 v[104:107], v[166:169], v[198:201], v[104:107]
	v_mfma_f32_16x16x32_f16 v[92:95], v[158:161], v[206:209], v[92:95]
	v_mfma_f32_16x16x32_f16 v[88:91], v[166:169], v[206:209], v[88:91]
	v_mfma_f32_16x16x32_f16 v[76:79], v[158:161], v[214:217], v[76:79]
	v_mfma_f32_16x16x32_f16 v[72:75], v[166:169], v[214:217], v[72:75]
	v_mfma_f32_16x16x32_f16 v[124:127], v[162:165], v[194:197], v[124:127]
	v_mfma_f32_16x16x32_f16 v[120:123], v[170:173], v[194:197], v[120:123]
	v_mfma_f32_16x16x32_f16 v[108:111], v[162:165], v[202:205], v[108:111]
	v_mfma_f32_16x16x32_f16 v[104:107], v[170:173], v[202:205], v[104:107]
	v_mfma_f32_16x16x32_f16 v[92:95], v[162:165], v[210:213], v[92:95]
	v_mfma_f32_16x16x32_f16 v[88:91], v[170:173], v[210:213], v[88:91]
	v_mfma_f32_16x16x32_f16 v[76:79], v[162:165], v[218:221], v[76:79]
	v_mfma_f32_16x16x32_f16 v[72:75], v[170:173], v[218:221], v[72:75]
	s_setprio 0
	s_setprio 1
	v_mfma_f32_16x16x32_f16 v[116:119], v[174:177], v[190:193], v[116:119]
	v_mfma_f32_16x16x32_f16 v[112:115], v[182:185], v[190:193], v[112:115]
	v_mfma_f32_16x16x32_f16 v[100:103], v[174:177], v[198:201], v[100:103]
	v_mfma_f32_16x16x32_f16 v[96:99], v[182:185], v[198:201], v[96:99]
	v_mfma_f32_16x16x32_f16 v[84:87], v[174:177], v[206:209], v[84:87]
	v_mfma_f32_16x16x32_f16 v[80:83], v[182:185], v[206:209], v[80:83]
	v_mfma_f32_16x16x32_f16 v[68:71], v[174:177], v[214:217], v[68:71]
	v_mfma_f32_16x16x32_f16 v[64:67], v[182:185], v[214:217], v[64:67]
	v_mfma_f32_16x16x32_f16 v[116:119], v[178:181], v[194:197], v[116:119]
	v_mfma_f32_16x16x32_f16 v[112:115], v[186:189], v[194:197], v[112:115]
	v_mfma_f32_16x16x32_f16 v[100:103], v[178:181], v[202:205], v[100:103]
	v_mfma_f32_16x16x32_f16 v[96:99], v[186:189], v[202:205], v[96:99]
	v_mfma_f32_16x16x32_f16 v[84:87], v[178:181], v[210:213], v[84:87]
	v_mfma_f32_16x16x32_f16 v[80:83], v[186:189], v[210:213], v[80:83]
	v_mfma_f32_16x16x32_f16 v[68:71], v[178:181], v[218:221], v[68:71]
	v_mfma_f32_16x16x32_f16 v[64:67], v[186:189], v[218:221], v[64:67]
	s_setprio 0
	s_barrier
	s_add_i32 s34, s48, s3
	v_lshl_add_u64 v[222:223], v[222:223], 0, s[10:11]
	s_mov_b32 m0, s34
	ds_read_b128 v[190:193], v153 offset:49152
	ds_read_b128 v[194:197], v153 offset:50176
	ds_read_b128 v[198:201], v153 offset:51200
	ds_read_b128 v[202:205], v153 offset:52224
	ds_read_b128 v[206:209], v153 offset:53248
	ds_read_b128 v[210:213], v153 offset:54272
	ds_read_b128 v[214:217], v153 offset:55296
	ds_read_b128 v[218:221], v153 offset:56320
	global_load_lds_dwordx4 v[222:223], off
	s_add_i32 m0, s34, 0x2000
	s_add_u32 s30, s30, 0x40080
	v_lshl_add_u64 v[222:223], v[224:225], 0, s[10:11]
	s_addc_u32 s31, s31, 0
	s_add_i32 s34, s49, s3
	global_load_lds_dwordx4 v[222:223], off
	v_lshl_add_u64 v[222:223], s[30:31], 0, v[132:133]
	s_mov_b32 m0, s34
	s_nop 0
	global_load_lds_dwordx4 v[222:223], off
	v_lshl_add_u64 v[222:223], s[30:31], 0, v[128:129]
	s_add_i32 m0, s34, 0x2000
	s_nop 0
	global_load_lds_dwordx4 v[222:223], off
	v_lshl_add_u64 v[222:223], v[226:227], 0, s[10:11]
	s_mov_b32 m0, s43
	s_nop 0
	global_load_lds_dwordx4 v[222:223], off
	v_lshl_add_u64 v[222:223], v[228:229], 0, s[10:11]
	s_mov_b32 m0, s44
	s_nop 0
	global_load_lds_dwordx4 v[222:223], off
	s_waitcnt vmcnt(8)
	s_waitcnt lgkmcnt(0)
	s_barrier
	s_setprio 1
	s_waitcnt lgkmcnt(0)
	v_mfma_f32_16x16x32_f16 v[60:63], v[158:161], v[190:193], v[60:63]
	v_mfma_f32_16x16x32_f16 v[56:59], v[166:169], v[190:193], v[56:59]
	v_mfma_f32_16x16x32_f16 v[44:47], v[158:161], v[198:201], v[44:47]
	v_mfma_f32_16x16x32_f16 v[40:43], v[166:169], v[198:201], v[40:43]
	v_mfma_f32_16x16x32_f16 v[28:31], v[158:161], v[206:209], v[28:31]
	v_mfma_f32_16x16x32_f16 v[24:27], v[166:169], v[206:209], v[24:27]
	v_mfma_f32_16x16x32_f16 v[12:15], v[158:161], v[214:217], v[12:15]
	v_mfma_f32_16x16x32_f16 v[8:11], v[166:169], v[214:217], v[8:11]
	v_mfma_f32_16x16x32_f16 v[60:63], v[162:165], v[194:197], v[60:63]
	v_mfma_f32_16x16x32_f16 v[56:59], v[170:173], v[194:197], v[56:59]
	v_mfma_f32_16x16x32_f16 v[44:47], v[162:165], v[202:205], v[44:47]
	v_mfma_f32_16x16x32_f16 v[40:43], v[170:173], v[202:205], v[40:43]
	v_mfma_f32_16x16x32_f16 v[28:31], v[162:165], v[210:213], v[28:31]
	v_mfma_f32_16x16x32_f16 v[24:27], v[170:173], v[210:213], v[24:27]
	v_mfma_f32_16x16x32_f16 v[12:15], v[162:165], v[218:221], v[12:15]
	v_mfma_f32_16x16x32_f16 v[8:11], v[170:173], v[218:221], v[8:11]
	s_setprio 0
	s_setprio 1
	v_mfma_f32_16x16x32_f16 v[52:55], v[174:177], v[190:193], v[52:55]
	v_mfma_f32_16x16x32_f16 v[48:51], v[182:185], v[190:193], v[48:51]
	v_mfma_f32_16x16x32_f16 v[36:39], v[174:177], v[198:201], v[36:39]
	v_mfma_f32_16x16x32_f16 v[32:35], v[182:185], v[198:201], v[32:35]
	v_mfma_f32_16x16x32_f16 v[20:23], v[174:177], v[206:209], v[20:23]
	v_mfma_f32_16x16x32_f16 v[16:19], v[182:185], v[206:209], v[16:19]
	v_mfma_f32_16x16x32_f16 v[4:7], v[174:177], v[214:217], v[4:7]
	v_mfma_f32_16x16x32_f16 v[0:3], v[182:185], v[214:217], v[0:3]
	v_mfma_f32_16x16x32_f16 v[52:55], v[178:181], v[194:197], v[52:55]
	v_mfma_f32_16x16x32_f16 v[48:51], v[186:189], v[194:197], v[48:51]
	v_mfma_f32_16x16x32_f16 v[36:39], v[178:181], v[202:205], v[36:39]
	v_mfma_f32_16x16x32_f16 v[32:35], v[186:189], v[202:205], v[32:35]
	v_mfma_f32_16x16x32_f16 v[20:23], v[178:181], v[210:213], v[20:23]
	v_mfma_f32_16x16x32_f16 v[16:19], v[186:189], v[210:213], v[16:19]
	v_mfma_f32_16x16x32_f16 v[4:7], v[178:181], v[218:221], v[4:7]
	v_mfma_f32_16x16x32_f16 v[0:3], v[186:189], v[218:221], v[0:3]
	s_setprio 0
	s_barrier
	s_add_i32 s51, s51, 2
	s_add_u32 s22, s22, 0x100
	s_addc_u32 s23, s23, 0
	s_add_u32 s13, s13, 0x100
	s_addc_u32 s15, s15, 0
	s_cmp_gt_u32 s51, 13
	s_cbranch_scc0 .LBB0_1429
	s_and_b64 vcc, exec, s[26:27]
	s_cbranch_vccz .LBB0_1432
	s_barrier
